# MLA attention V^T LDS tile: 144-byte rows and per-half-contiguous key order so each PV fragment is one ds_read_b128 instead of ds_read2_b64
# speedup vs baseline: 1.0036x; 1.0036x over previous
;     ...
;     auto lstore = [&](const u32x4 (&rk)[KCH], const u32x4 (&rv)[2], const float rf, int buf) {
;       bf16_t* kd = Kl + buf * 64 * KST + lkey * KST + lsub * 8;
;       *(u32x4*)kd = rk[0]; *(u32x4*)(kd + 32) = rk[1];
;       if (MODE == 1) *(u32x4*)(kd + 64) = rk[KCH - 1];
;       bf16_t* vd = Vl + buf * 64 * VST + lkey * VST + lsub * 8;
;       u32x2 lo, hi;
;       lo[0] = rv[0][0]; lo[1] = rv[0][1]; hi[0] = rv[0][2]; hi[1] = rv[0][3];
;       *(u32x2*)vd = lo; *(u32x2*)(vd + 4) = hi;
;       lo[0] = rv[1][0]; lo[1] = rv[1][1]; hi[0] = rv[1][2]; hi[1] = rv[1][3];
;       *(u32x2*)(vd + 32) = lo; *(u32x2*)(vd + 36) = hi;
;       if (MODE == 2 && t < 64) Fl[buf * 64 + t] = -rf * LOG2E;
;     };
;     ...
;         auto ldv = [&](int j) {
; #pragma unroll
;           for (int st = 0; st < 2; ++st)
; #pragma unroll
;             for (int dt = 0; dt < 2; ++dt) {
;               const bf16_t* vp = Vb + (dt * 32 + r) * VST + j * 32 + 16 * st + 4 * hh;
;               const u32x2 lo = *(const u32x2*)vp, hi = *(const u32x2*)(vp + 8);
;               vfr[st][dt][0] = lo[0]; vfr[st][dt][1] = lo[1]; vfr[st][dt][2] = hi[0]; vfr[st][dt][3] = hi[1];
;             }
;           __builtin_amdgcn_sched_barrier(0);
;         };
.LBB0_814:
	s_andn2_b64 vcc, exec, s[4:5]
	s_cbranch_vccnz .LBB0_910
	v_mov_b32_e32 v1, v172
	s_movk_i32 s1, 0xd0
	v_and_b32_e32 v150, 31, v1
	v_bfe_u32 v3, v1, 5, 1
	s_waitcnt vmcnt(0)
	v_ashrrev_i32_e32 v187, 2, v1
	v_cmp_eq_u32_e64 s[42:43], 0, v1
	v_ashrrev_i32_e32 v0, 1, v1
	v_lshlrev_b32_e32 v1, 3, v1
	v_and_b32_e32 v2, 24, v1
	v_lshlrev_b32_e32 v144, 1, v2
	v_mad_u64_u32 v[152:153], s[4:5], v187, s1, v[144:145]
	s_movk_i32 s1, 0xffb8
	v_mul_u32_u24_e32 v1, 0x68, v150
	v_and_b32_e32 v188, 0xffffffe0, v0
	v_lshlrev_b32_e32 v0, 3, v3
	v_mad_u64_u32 v[154:155], s[4:5], v187, s1, v[152:153]
	v_lshlrev_b32_e32 v1, 1, v1
	v_mul_i32_i24_e32 v5, 0xffffffb8, v150
	v_lshl_add_u32 v153, v3, 4, v1
	v_add3_u32 v155, v1, v5, v0
	v_lshrrev_b32_e32 v230, 2, v172
	v_mul_u32_u24_e32 v154, 0x90, v230
	v_bfe_u32 v230, v172, 1, 1
	v_lshl_add_u32 v154, v230, 5, v154
	v_and_b32_e32 v230, 1, v172
	v_lshl_add_u32 v154, v230, 3, v154
	v_and_b32_e32 v230, 31, v172
	v_mul_u32_u24_e32 v155, 0x90, v230
	v_bfe_u32 v230, v172, 5, 1
	v_lshl_add_u32 v155, v230, 4, v155
	v_cvt_f32_ubyte0_e32 v1, v0
	v_mul_f32_e32 v1, 0xbf549a78, v1
	v_exp_f32_e32 v189, v1
	v_or_b32_e32 v1, 1, v0
	v_cvt_f32_ubyte0_e32 v1, v1
	v_mul_f32_e32 v1, 0xbf549a78, v1
	v_exp_f32_e32 v190, v1
	v_or_b32_e32 v1, 2, v0
	v_cvt_f32_ubyte0_e32 v1, v1
	v_mul_f32_e32 v1, 0xbf549a78, v1
	v_exp_f32_e32 v191, v1
	v_or_b32_e32 v1, 3, v0
	v_cvt_f32_ubyte0_e32 v1, v1
	v_mul_f32_e32 v1, 0xbf549a78, v1
	v_exp_f32_e32 v192, v1
	v_or_b32_e32 v1, 4, v0
	v_cvt_f32_ubyte0_e32 v1, v1
	v_mul_f32_e32 v1, 0xbf549a78, v1
	v_exp_f32_e32 v193, v1
	v_or_b32_e32 v1, 5, v0
	v_cvt_f32_ubyte0_e32 v1, v1
	v_mul_f32_e32 v1, 0xbf549a78, v1
	v_exp_f32_e32 v194, v1
	v_or_b32_e32 v1, 6, v0
	v_cvt_f32_ubyte0_e32 v1, v1
	v_mul_f32_e32 v1, 0xbf549a78, v1
	v_exp_f32_e32 v195, v1
	v_or_b32_e32 v1, 7, v0
	v_cvt_f32_ubyte0_e32 v1, v1
	v_mul_f32_e32 v1, 0xbf549a78, v1
	v_exp_f32_e32 v196, v1
	v_readlane_b32 s4, v228, 6
	v_readlane_b32 s24, v228, 4
	v_lshlrev_b32_e32 v4, 2, v3
	v_readlane_b32 s5, v228, 7
	v_readlane_b32 s25, v228, 5
	v_mad_i32_i24 v1, v3, -4, v188
	s_movk_i32 s1, 0x2040
	s_getreg_b32 s14, hwreg(HW_REG_XCC_ID, 0, 4)
	s_mov_b32 s15, 0
	v_lshl_add_u64 v[156:157], s[4:5], 0, v[144:145]
	v_lshl_add_u64 v[158:159], s[64:65], 0, v[144:145]
	v_lshl_add_u64 v[160:161], s[24:25], 0, v[144:145]
	v_add3_u32 v197, v1, v150, s1
	v_lshlrev_b32_e32 v144, 1, v0
	v_lshlrev_b32_e32 v162, 1, v2
	v_lshlrev_b32_e32 v164, 1, v4
	s_branch .LBB0_817

; DI float bf2f(short s) { return __uint_as_float(((unsigned)(unsigned short)s) << 16); }
; DI float fexp2(float x) { return __builtin_amdgcn_exp2f(x); }
;     ...
;     __syncthreads();
;     if (t == 0) {
;       int v = -1;
;       while (qx < 8) {
;         const int xx = (myx + qx) & 7;
;         const int got = (int)atomicAdd(aa.ctr + xx, 1u);
;         if (got < total / 8) { v = got * 8 + xx; break; }
;         ++qx;
;       }
;       s_item[0] = v; s_item[1] = qx;
;     }
;     __syncthreads();
;     const int enc = s_item[0]; qx = s_item[1];
;     if (enc < 0) break;
;     const int xx_ = enc & 7, idx = enc >> 3;
;     const int qt = 64 - idx % 65, bh = (idx / 65) * 8 + xx_, b = bh >> 4, hd = bh & 15;
;     const int q0 = qt * 128;
;     const int posq = q0 + w * 32 + r;
;     const bool qvalid = posq < L;
;     const int pq = qvalid ? posq : L - 1;
;     bf16_t* qptr = aa.q + (size_t)(b * L + pq) * aa.ldq + hd * aa.hs;
;     bf16x8 qf[NKS];
; #pragma unroll
;     for (int ks = 0; ks < NKS; ++ks) qf[ks] = *(const bf16x8*)(qptr + ks * 16 + 8 * hh);
;     if (MODE == 1) {
; #pragma unroll
;       for (int j = 0; j < 8; j += 2) {
;         float o1[2], o2[2];
; #pragma unroll
;         for (int e = 0; e < 2; ++e) {
;           const int i = 8 * hh + j + e;
;           const float inv = fexp2(-(float)i * 0.83048202f);
;           const float ang = (float)pq * inv;
;           const float n = rintf(ang * 0.15915494f);
;           float rr = fmaf(-n, 6.2831855f, ang); rr = fmaf(-n, -1.7484555e-7f, rr);
;           const float cs = __cosf(rr), sn = __sinf(rr);
;           const float x1 = bf2f(qf[NKS - 2][j + e]), x2 = bf2f(qf[NKS - 1][j + e]);
;           o1[e] = x1 * cs - x2 * sn; o2[e] = x2 * cs + x1 * sn;
;         }
;         const unsigned p1 = pk_bf16(o1[0], o1[1]), p2 = pk_bf16(o2[0], o2[1]);
;         qf[NKS - 2][j] = (short)(p1 & 0xffff); qf[NKS - 2][j + 1] = (short)(p1 >> 16);
;         qf[NKS - 1][j] = (short)(p2 & 0xffff); qf[NKS - 1][j + 1] = (short)(p2 >> 16);
;       }
;     }
.LBB0_825:
	s_or_b64 exec, exec, s[6:7]
	s_xor_b64 s[6:7], s[8:9], -1
	v_mov_b32_e32 v0, -1
	s_and_saveexec_b64 s[8:9], s[6:7]
	s_xor_b64 s[6:7], exec, s[8:9]
	v_lshl_or_b32 v0, v2, 3, v3
	s_or_b64 exec, exec, s[6:7]
	ds_write_b64 v145, v[0:1] offset:45568
.LBB0_828:
	s_or_b64 exec, exec, s[4:5]
	s_waitcnt lgkmcnt(0)
	s_barrier
	ds_read_b64 v[0:1], v145 offset:45568
	s_waitcnt lgkmcnt(0)
	v_readfirstlane_b32 s1, v0
	s_cmp_lt_i32 s1, 0
	v_readfirstlane_b32 s15, v1
	s_cbranch_scc1 .LBB0_859
	s_lshr_b32 s6, s1, 3
	s_mul_hi_u32 s5, s6, 0x3f03f04
	s_mulk_i32 s5, 0x41
	s_and_b32 s4, s1, 7
	s_sub_i32 s5, s6, s5
	s_mul_hi_u32 s1, s1, 0xfc0fc0fd
	s_lshr_b32 s7, s1, 9
	s_lshr_b32 s10, s1, 10
	s_lshl_b32 s1, s5, 7
	v_subrev_u32_e32 v8, s1, v188
	s_lshl_b32 s8, s7, 3
	v_add_u32_e32 v165, 0x2000, v8
	s_or_b32 s8, s8, s4
	v_or_b32_e32 v0, v165, v150
	s_movk_i32 s4, 0x2010
	v_cmp_gt_i32_e64 s[44:45], s4, v0
	s_mulk_i32 s10, 0x2010
	s_and_b32 s9, s8, 15
	v_cndmask_b32_e64 v9, v186, v0, s[44:45]
	v_add_u32_e32 v2, s10, v9
	v_mov_b64_e32 v[0:1], s[68:69]
	s_movk_i32 s4, 0xc00
	v_mad_i64_i32 v[0:1], s[4:5], v2, s4, v[0:1]
	s_mul_i32 s18, s9, 0xc0
	v_lshl_add_u64 v[166:167], v[0:1], 0, s[18:19]
	v_lshl_add_u64 v[4:5], v[166:167], 0, v[144:145]
	global_load_dwordx4 v[64:67], v[4:5], off
	global_load_dwordx4 v[68:71], v[4:5], off offset:32
	global_load_dwordx4 v[72:75], v[4:5], off offset:64
	global_load_dwordx4 v[76:79], v[4:5], off offset:96
	global_load_dwordx4 v[0:3], v[4:5], off offset:128
	s_nop 0
	global_load_dwordx4 v[4:7], v[4:5], off offset:160
	v_cvt_f32_i32_e32 v9, v9
	s_sub_i32 s1, 0x2040, s1
	s_lshr_b32 s1, s1, 6
	s_min_u32 s1, s1, 0x80
	v_mul_f32_e32 v10, v189, v9
	v_mul_f32_e32 v11, 0.15915494, v10
	v_rndne_f32_e32 v11, v11
	v_fmac_f32_e32 v10, 0xc0c90fdb, v11
	v_fmac_f32_e32 v10, 0x343bbd2e, v11
	v_mul_f32_e32 v11, 0.15915494, v10
	v_cos_f32_e32 v10, v11
	v_sin_f32_e32 v12, v11
	v_mul_f32_e32 v11, v190, v9
	v_mul_f32_e32 v13, 0.15915494, v11
	v_rndne_f32_e32 v13, v13
	v_fmac_f32_e32 v11, 0xc0c90fdb, v13
	v_fmac_f32_e32 v11, 0x343bbd2e, v13
	v_mul_f32_e32 v13, 0.15915494, v11
	v_cos_f32_e32 v11, v13
	v_sin_f32_e32 v13, v13
	s_lshl_b32 s18, s9, 7
	v_mov_b32_e32 v163, v145
	s_waitcnt vmcnt(1)
	v_and_b32_e32 v15, 0xffff0000, v0
	v_lshlrev_b32_e32 v14, 16, v0
	v_mul_f32_e32 v0, v191, v9
	s_waitcnt vmcnt(0)
;     ...
;     if (MODE == 1) {
; #pragma unroll
;       for (int j = 0; j < 8; j += 2) {
;         float o1[2], o2[2];
; #pragma unroll
;         for (int e = 0; e < 2; ++e) {
;           const int i = 8 * hh + j + e;
;           const float inv = fexp2(-(float)i * 0.83048202f);
;           const float ang = (float)pq * inv;
;           const float n = rintf(ang * 0.15915494f);
;           float rr = fmaf(-n, 6.2831855f, ang); rr = fmaf(-n, -1.7484555e-7f, rr);
;           const float cs = __cosf(rr), sn = __sinf(rr);
;           const float x1 = bf2f(qf[NKS - 2][j + e]), x2 = bf2f(qf[NKS - 1][j + e]);
;           o1[e] = x1 * cs - x2 * sn; o2[e] = x2 * cs + x1 * sn;
;         }
;         const unsigned p1 = pk_bf16(o1[0], o1[1]), p2 = pk_bf16(o2[0], o2[1]);
;         qf[NKS - 2][j] = (short)(p1 & 0xffff); qf[NKS - 2][j + 1] = (short)(p1 >> 16);
;         qf[NKS - 1][j] = (short)(p2 & 0xffff); qf[NKS - 1][j + 1] = (short)(p2 >> 16);
;       }
;     }
;     ...
;     auto gload = [&](u32x4 (&rk)[KCH], u32x4 (&rv)[2], float& rf, int ktile) {
;       int kp = ktile * 64 + lkey; kp = kp < L ? kp : L - 1;
;       const size_t mk = (size_t)(b * L + kp);
;       const bf16_t* ks_ = aa.k + mk * D + hd * 64 + lsub * 8;
;       rk[0] = *(const u32x4*)ks_; __builtin_amdgcn_sched_barrier(0);
;       rk[1] = *(const u32x4*)(ks_ + 32); __builtin_amdgcn_sched_barrier(0);
;       if (MODE == 1) { rk[KCH - 1] = *(const u32x4*)(aa.kr + mk * 32 + lsub * 8); __builtin_amdgcn_sched_barrier(0); }
;       rv[0] = *(const u32x4*)(vsrc + ktile * 64); __builtin_amdgcn_sched_barrier(0);
;       rv[1] = *(const u32x4*)(vsrc + ktile * 64 + 32); __builtin_amdgcn_sched_barrier(0);
;       if (MODE == 2) { rf = aa.Fh[(size_t)bh * LP + ktile * 64 + (t & 63)]; __builtin_amdgcn_sched_barrier(0); }
;     };
;     auto lstore = [&](const u32x4 (&rk)[KCH], const u32x4 (&rv)[2], const float rf, int buf) {
;       bf16_t* kd = Kl + buf * 64 * KST + lkey * KST + lsub * 8;
;       *(u32x4*)kd = rk[0]; *(u32x4*)(kd + 32) = rk[1];
;       if (MODE == 1) *(u32x4*)(kd + 64) = rk[KCH - 1];
;       bf16_t* vd = Vl + buf * 64 * VST + lkey * VST + lsub * 8;
;       u32x2 lo, hi;
;       lo[0] = rv[0][0]; lo[1] = rv[0][1]; hi[0] = rv[0][2]; hi[1] = rv[0][3];
;       *(u32x2*)vd = lo; *(u32x2*)(vd + 4) = hi;
;       lo[0] = rv[1][0]; lo[1] = rv[1][1]; hi[0] = rv[1][2]; hi[1] = rv[1][3];
	v_and_b32_e32 v17, 0xffff0000, v4
	v_lshlrev_b32_e32 v16, 16, v4
	v_mul_f32_e32 v4, 0.15915494, v0
	v_rndne_f32_e32 v4, v4
	v_pk_mul_f32 v[18:19], v[12:13], v[16:17]
	v_fmac_f32_e32 v0, 0xc0c90fdb, v4
	v_pk_fma_f32 v[18:19], v[10:11], v[14:15], v[18:19] neg_lo:[0,0,1] neg_hi:[0,0,1]
	v_pk_mul_f32 v[10:11], v[10:11], v[16:17]
	v_fmac_f32_e32 v0, 0x343bbd2e, v4
	v_pk_fma_f32 v[10:11], v[12:13], v[14:15], v[10:11]
	v_mul_f32_e32 v0, 0.15915494, v0
	v_cvt_pk_bf16_f32 v84, v10, v11
	v_cos_f32_e32 v10, v0
	v_sin_f32_e32 v12, v0
	v_mul_f32_e32 v0, v192, v9
	v_mul_f32_e32 v4, 0.15915494, v0
	v_rndne_f32_e32 v4, v4
	v_fmac_f32_e32 v0, 0xc0c90fdb, v4
	v_fmac_f32_e32 v0, 0x343bbd2e, v4
	v_mul_f32_e32 v0, 0.15915494, v0
	v_cos_f32_e32 v11, v0
	v_sin_f32_e32 v13, v0
	v_and_b32_e32 v15, 0xffff0000, v1
	v_lshlrev_b32_e32 v14, 16, v1
	v_and_b32_e32 v1, 0xffff0000, v5
	v_lshlrev_b32_e32 v0, 16, v5
	v_pk_mul_f32 v[4:5], v[12:13], v[0:1]
	v_pk_mul_f32 v[0:1], v[10:11], v[0:1]
	v_pk_fma_f32 v[4:5], v[10:11], v[14:15], v[4:5] neg_lo:[0,0,1] neg_hi:[0,0,1]
	v_pk_fma_f32 v[0:1], v[12:13], v[14:15], v[0:1]
	v_cvt_pk_bf16_f32 v81, v4, v5
	v_cvt_pk_bf16_f32 v85, v0, v1
	v_mul_f32_e32 v0, v193, v9
	v_mul_f32_e32 v1, 0.15915494, v0
	v_rndne_f32_e32 v1, v1
	v_fmac_f32_e32 v0, 0xc0c90fdb, v1
	v_fmac_f32_e32 v0, 0x343bbd2e, v1
	v_mul_f32_e32 v1, 0.15915494, v0
	v_cos_f32_e32 v0, v1
	v_sin_f32_e32 v4, v1
	v_mul_f32_e32 v1, v194, v9
	v_mul_f32_e32 v5, 0.15915494, v1
	v_rndne_f32_e32 v5, v5
	v_fmac_f32_e32 v1, 0xc0c90fdb, v5
	v_fmac_f32_e32 v1, 0x343bbd2e, v5
	v_mul_f32_e32 v5, 0.15915494, v1
	v_cos_f32_e32 v1, v5
	v_sin_f32_e32 v5, v5
	v_and_b32_e32 v13, 0xffff0000, v6
	v_lshlrev_b32_e32 v12, 16, v6
	v_and_b32_e32 v11, 0xffff0000, v2
	v_lshlrev_b32_e32 v10, 16, v2
	v_pk_mul_f32 v[14:15], v[4:5], v[12:13]
	v_cvt_pk_bf16_f32 v80, v18, v19
	v_pk_fma_f32 v[14:15], v[0:1], v[10:11], v[14:15] neg_lo:[0,0,1] neg_hi:[0,0,1]
	v_pk_mul_f32 v[0:1], v[0:1], v[12:13]
	v_cvt_pk_bf16_f32 v82, v14, v15
	v_pk_fma_f32 v[0:1], v[4:5], v[10:11], v[0:1]
	v_and_b32_e32 v11, 0xffff0000, v3
	v_cvt_pk_bf16_f32 v86, v0, v1
	v_mul_f32_e32 v0, v195, v9
	v_mul_f32_e32 v1, 0.15915494, v0
	v_rndne_f32_e32 v1, v1
	v_fmac_f32_e32 v0, 0xc0c90fdb, v1
	v_fmac_f32_e32 v0, 0x343bbd2e, v1
	v_mul_f32_e32 v1, 0.15915494, v0
	v_cos_f32_e32 v0, v1
	v_sin_f32_e32 v4, v1
	v_mul_f32_e32 v1, v196, v9
	v_mul_f32_e32 v2, 0.15915494, v1
	v_rndne_f32_e32 v2, v2
	v_fmac_f32_e32 v1, 0xc0c90fdb, v2
	v_fmac_f32_e32 v1, 0x343bbd2e, v2
	v_mul_f32_e32 v2, 0.15915494, v1
	v_sin_f32_e32 v5, v2
	v_cos_f32_e32 v1, v2
	v_lshlrev_b32_e32 v10, 16, v3
	v_and_b32_e32 v3, 0xffff0000, v7
	v_lshlrev_b32_e32 v2, 16, v7
	v_pk_mul_f32 v[6:7], v[4:5], v[2:3]
	s_nop 0
	v_pk_fma_f32 v[6:7], v[0:1], v[10:11], v[6:7] neg_lo:[0,0,1] neg_hi:[0,0,1]
	v_pk_mul_f32 v[0:1], v[0:1], v[2:3]
	v_cvt_pk_bf16_f32 v83, v6, v7
	v_pk_fma_f32 v[0:1], v[4:5], v[10:11], v[0:1]
	s_nop 0
	v_cvt_pk_bf16_f32 v87, v0, v1
	v_lshl_add_u32 v0, s8, 6, v187
	s_lshl_b32 s8, s1, 6
	v_mad_i64_i32 v[168:169], s[4:5], v0, s27, v[156:157]
	v_add_u32_e32 v0, s8, v187
	v_min_i32_e32 v0, 0x200f, v0
	v_add_u32_e32 v4, s10, v0
	v_ashrrev_i32_e32 v5, 31, v4
	v_lshlrev_b64 v[0:1], 11, v[4:5]
	v_lshl_add_u64 v[0:1], s[24:25], 0, v[0:1]
	v_lshl_add_u64 v[0:1], v[0:1], 0, s[18:19]
	v_lshl_add_u64 v[6:7], v[0:1], 0, v[162:163]
	global_load_dwordx4 v[0:3], v[6:7], off
	global_load_dwordx4 v[10:13], v[6:7], off offset:64
	v_lshlrev_b64 v[4:5], 6, v[4:5]
	v_lshl_add_u64 v[4:5], v[158:159], 0, v[4:5]
	global_load_dwordx4 v[4:7], v[4:5], off
	s_lshl_b32 s4, s1, 7
	s_mov_b32 s5, s19
	v_lshl_add_u64 v[18:19], v[168:169], 0, s[4:5]
	global_load_dwordx4 v[14:17], v[18:19], off
	s_nop 0
	global_load_dwordx4 v[18:21], v[18:19], off offset:64
	s_sub_i32 s4, s8, 64
	v_add_u32_e32 v9, s4, v187
	v_min_i32_e32 v9, 0x200f, v9
	v_add_u32_e32 v22, s10, v9
	v_ashrrev_i32_e32 v23, 31, v22
	v_lshlrev_b64 v[24:25], 11, v[22:23]
	v_lshl_add_u64 v[24:25], s[24:25], 0, v[24:25]
	v_lshl_add_u64 v[24:25], v[24:25], 0, s[18:19]
	v_lshl_add_u64 v[24:25], v[24:25], 0, v[162:163]
	global_load_dwordx4 v[88:91], v[24:25], off
	global_load_dwordx4 v[92:95], v[24:25], off offset:64
	v_lshlrev_b64 v[22:23], 6, v[22:23]
	v_lshl_add_u64 v[22:23], v[158:159], 0, v[22:23]
	global_load_dwordx4 v[96:99], v[22:23], off
	v_lshl_add_u64 v[22:23], s[4:5], 1, v[168:169]
	global_load_dwordx4 v[104:107], v[22:23], off
	global_load_dwordx4 v[100:103], v[22:23], off offset:64
	s_mulk_i32 s7, 0x2080
	s_waitcnt vmcnt(9)
	ds_write_b128 v152, v[0:3]
	s_waitcnt vmcnt(8)
	ds_write_b128 v152, v[10:13] offset:64
	s_waitcnt vmcnt(7)
	ds_write_b128 v152, v[4:7] offset:128
	v_add_u32_e32 v163, 0x6800, v154
	v_add_u32_e32 v0, s7, v197
	s_waitcnt vmcnt(6)
	ds_write2_b64 v163, v[14:15], v[16:17] offset1:2
	v_add_u32_e32 v198, 0x6840, v154
	v_subrev_u32_e32 v0, s8, v0
	s_lshl_b32 s5, s6, 7
	v_mov_b32_e32 v14, v145
	v_mov_b32_e32 v15, v145
	s_waitcnt vmcnt(5)
	ds_write2_b64 v198, v[18:19], v[20:21] offset1:2
	v_add_u32_e32 v199, 0x201f, v8
	v_subrev_u32_e32 v200, s5, v0
	v_mov_b32_e32 v0, v145
	v_mov_b32_e32 v1, v145
	v_mov_b32_e32 v2, v145
	v_mov_b32_e32 v3, v145
	v_mov_b32_e32 v4, v145
	v_mov_b32_e32 v5, v145
	v_mov_b32_e32 v6, v145
	v_mov_b32_e32 v7, v145
	v_mov_b32_e32 v8, v145
	v_mov_b32_e32 v9, v145
	v_mov_b32_e32 v10, v145
	v_mov_b32_e32 v11, v145
	v_mov_b32_e32 v12, v145
	v_mov_b32_e32 v13, v145
	v_mov_b64_e32 v[30:31], v[14:15]
	v_lshl_add_u64 v[170:171], v[160:161], 0, s[18:19]
	v_mov_b32_e32 v203, 0xf149f2ca
	v_mov_b32_e32 v201, 0
	v_mov_b64_e32 v[28:29], v[12:13]
	v_mov_b64_e32 v[26:27], v[10:11]
	v_mov_b64_e32 v[24:25], v[8:9]
	v_mov_b64_e32 v[22:23], v[6:7]
	v_mov_b64_e32 v[20:21], v[4:5]
	v_mov_b64_e32 v[18:19], v[2:3]
	v_mov_b64_e32 v[16:17], v[0:1]
	s_branch .LBB0_834

; #define MFMA32(a, b, c) __builtin_amdgcn_mfma_f32_32x32x16_bf16((a), (b), (c), 0, 0, 0)
;     ...
;       { const int kpre = kt > 1 ? kt - 2 : 0; if (PAR == 0) gload(rkA, rvA, rfA, kpre); else gload(rkB, rvB, rfB, kpre); }
;       if (kt * 64 <= wqmax && dry < 2) {
;         const bf16_t* Kb = Kl + buf * 64 * KST; const bf16_t* Vb = Vl + buf * 64 * VST;
;         f32x16 s[2];
; #pragma unroll
;         for (int i = 0; i < 16; ++i) { s[0][i] = 0.f; s[1][i] = 0.f; }
;         if (MODE == 0) {
; #pragma unroll
;           for (int ks = 0; ks < NKS; ++ks) {
;             const bf16x8 a0 = *(const bf16x8*)(Kb + r * KST + ks * 16 + 8 * hh);
;             const bf16x8 a1 = *(const bf16x8*)(Kb + (32 + r) * KST + ks * 16 + 8 * hh);
;             s[0] = MFMA32(a0, qf[ks], s[0]);
;             s[1] = MFMA32(a1, qf[ks], s[1]);
;           }
;         } else {
;           bf16x8 kf0[NKS], kf1[NKS];
; #pragma unroll
;           for (int ks = 0; ks < NKS; ++ks) kf0[ks] = *(const bf16x8*)(Kb + r * KST + ks * 16 + 8 * hh);
; #pragma unroll
;           for (int ks = 0; ks < NKS; ++ks) kf1[ks] = *(const bf16x8*)(Kb + (32 + r) * KST + ks * 16 + 8 * hh);
;           __builtin_amdgcn_sched_barrier(0);
; #pragma unroll
;           for (int ks = 0; ks < NKS; ++ks) s[0] = MFMA32(kf0[ks], qf[ks], s[0]);
; #pragma unroll
;           for (int ks = 0; ks < NKS; ++ks) s[1] = MFMA32(kf1[ks], qf[ks], s[1]);
;           __builtin_amdgcn_sched_barrier(0);
;         }
;         const int kbase = kt * 64 + 4 * hh;
;         u32x4 vfr[2][2];
;         auto ldv = [&](int j) {
; #pragma unroll
;           for (int st = 0; st < 2; ++st)
; #pragma unroll
;             for (int dt = 0; dt < 2; ++dt) {
;               const bf16_t* vp = Vb + (dt * 32 + r) * VST + j * 32 + 16 * st + 4 * hh;
;               const u32x2 lo = *(const u32x2*)vp, hi = *(const u32x2*)(vp + 8);
;               vfr[st][dt][0] = lo[0]; vfr[st][dt][1] = lo[1]; vfr[st][dt][2] = hi[0]; vfr[st][dt][3] = hi[1];
;             }
;           __builtin_amdgcn_sched_barrier(0);
;         };
;     ...
;             if (diag) {
;               asm volatile("" ::: "memory");
; #pragma unroll
;               for (int i = 0; i < 16; ++i) s[j][i] = (j * 32 + 8 * (i >> 2) + (i & 3)) <= dq ? s[j][i] : -INFINITY;
;             }
.LBB0_833:
	s_or_b64 exec, exec, s[6:7]
	v_sub_co_u32_e64 v32, s[6:7], s1, 1
	s_addk_i32 s4, 0xff80
	v_add_u32_e32 v200, 0x80, v200
	v_readfirstlane_b32 s1, v32
	s_waitcnt vmcnt(9)
	ds_write_b128 v152, v[108:111]
	s_waitcnt vmcnt(8)
	ds_write_b128 v152, v[112:115] offset:64
	s_waitcnt vmcnt(7)
	ds_write_b128 v152, v[116:119] offset:128
	s_waitcnt vmcnt(6)
	ds_write2_b64 v163, v[120:121], v[122:123] offset1:2
	s_waitcnt vmcnt(5)
	ds_write2_b64 v198, v[124:125], v[126:127] offset1:2
	s_and_b64 vcc, exec, s[6:7]
	s_cbranch_vccnz .LBB0_857
.LBB0_834:
	s_max_i32 s5, s1, 2
	s_lshl_b32 s5, s5, 6
	s_add_i32 s18, s5, 0xffffff80
	v_add_u32_e32 v32, s18, v187
	v_min_i32_e32 v32, 0x200f, v32
	v_add_u32_e32 v32, s10, v32
	v_ashrrev_i32_e32 v33, 31, v32
	v_lshlrev_b64 v[34:35], 11, v[32:33]
	v_lshl_add_u64 v[34:35], v[170:171], 0, v[34:35]
	s_waitcnt lgkmcnt(0)
	s_barrier
	global_load_dwordx4 v[108:111], v[34:35], off
	global_load_dwordx4 v[112:115], v[34:35], off offset:64
	v_lshlrev_b64 v[32:33], 6, v[32:33]
	v_lshl_add_u64 v[32:33], v[158:159], 0, v[32:33]
	global_load_dwordx4 v[116:119], v[32:33], off
	v_lshl_add_u64 v[32:33], s[18:19], 1, v[168:169]
	global_load_dwordx4 v[120:123], v[32:33], off
	global_load_dwordx4 v[124:127], v[32:33], off offset:64
	s_add_i32 s5, s4, 64
	v_cmp_le_i32_e32 vcc, s5, v199
	s_and_saveexec_b64 s[6:7], vcc
	s_cbranch_execz .LBB0_846
	ds_read_b128 v[32:35], v153
	ds_read_b128 v[36:39], v153 offset:32
	ds_read_b128 v[40:43], v153 offset:64
	ds_read_b128 v[44:47], v153 offset:96
	ds_read_b128 v[128:131], v153 offset:128
	ds_read_b128 v[132:135], v153 offset:160
	ds_read_b128 v[136:139], v153 offset:6656
	ds_read_b128 v[140:143], v153 offset:6688
	ds_read_b128 v[204:207], v153 offset:6720
	ds_read_b128 v[208:211], v153 offset:6752
	ds_read_b128 v[212:215], v153 offset:6784
	ds_read_b128 v[216:219], v153 offset:6816
	s_waitcnt lgkmcnt(11)
	v_mfma_f32_32x32x16_bf16 v[48:63], v[32:35], v[64:67], 0
	s_waitcnt lgkmcnt(10)
	v_mfma_f32_32x32x16_bf16 v[48:63], v[36:39], v[68:71], v[48:63]
	s_waitcnt lgkmcnt(9)
	v_mfma_f32_32x32x16_bf16 v[48:63], v[40:43], v[72:75], v[48:63]
	s_waitcnt lgkmcnt(8)
	v_mfma_f32_32x32x16_bf16 v[48:63], v[44:47], v[76:79], v[48:63]
	s_waitcnt lgkmcnt(5)
	v_mfma_f32_32x32x16_bf16 v[32:47], v[136:139], v[64:67], 0
	s_waitcnt lgkmcnt(4)
	v_mfma_f32_32x32x16_bf16 v[32:47], v[140:143], v[68:71], v[32:47]
	s_waitcnt lgkmcnt(3)
	v_mfma_f32_32x32x16_bf16 v[32:47], v[204:207], v[72:75], v[32:47]
	s_waitcnt lgkmcnt(2)
	v_mfma_f32_32x32x16_bf16 v[32:47], v[208:211], v[76:79], v[32:47]
	v_mfma_f32_32x32x16_bf16 v[48:63], v[128:131], v[80:83], v[48:63]
	s_waitcnt lgkmcnt(1)
	v_mfma_f32_32x32x16_bf16 v[32:47], v[212:215], v[80:83], v[32:47]
	v_mfma_f32_32x32x16_bf16 v[48:63], v[132:135], v[84:87], v[48:63]
	s_waitcnt lgkmcnt(0)
	v_mfma_f32_32x32x16_bf16 v[32:47], v[216:219], v[84:87], v[32:47]
	v_add_u32_e32 v206, 0x6800, v155
	v_add_u32_e32 v207, 0x7800, v155
	ds_read_b128 v[140:143], v155 offset:26624
	ds_read_b128 v[128:131], v155 offset:26656
	ds_read_b128 v[136:139], v155 offset:31232
	ds_read_b128 v[132:135], v155 offset:31264
	s_add_i32 s5, s4, 0x7f
	v_cmp_gt_i32_e64 s[46:47], s5, v165
	v_subrev_u32_e32 v204, 64, v200
	s_and_saveexec_b64 s[8:9], s[46:47]
	s_cbranch_execz .LBB0_837
	v_cmp_lt_i32_e32 vcc, -1, v204
	s_nop 1
	v_cndmask_b32_e32 v48, v185, v48, vcc
	v_cmp_lt_i32_e32 vcc, 0, v204
	s_nop 1
	v_cndmask_b32_e32 v49, v185, v49, vcc
	v_cmp_lt_i32_e32 vcc, 1, v204
	s_nop 1
	v_cndmask_b32_e32 v50, v185, v50, vcc
	v_cmp_lt_i32_e32 vcc, 2, v204
	s_nop 1
	v_cndmask_b32_e32 v51, v185, v51, vcc
	v_cmp_lt_i32_e32 vcc, 7, v204
	s_nop 1
	v_cndmask_b32_e32 v52, v185, v52, vcc
	v_cmp_lt_i32_e32 vcc, 8, v204
	s_nop 1
	v_cndmask_b32_e32 v53, v185, v53, vcc
	v_cmp_lt_i32_e32 vcc, 9, v204
	s_nop 1
	v_cndmask_b32_e32 v54, v185, v54, vcc
	v_cmp_lt_i32_e32 vcc, 10, v204
	s_nop 1
	v_cndmask_b32_e32 v55, v185, v55, vcc
	v_cmp_lt_i32_e32 vcc, 15, v204
	s_nop 1
	v_cndmask_b32_e32 v56, v185, v56, vcc
	v_cmp_lt_i32_e32 vcc, 16, v204
	s_nop 1
	v_cndmask_b32_e32 v57, v185, v57, vcc
	v_cmp_lt_i32_e32 vcc, 17, v204
	s_nop 1
	v_cndmask_b32_e32 v58, v185, v58, vcc
	v_cmp_lt_i32_e32 vcc, 18, v204
	s_nop 1
	v_cndmask_b32_e32 v59, v185, v59, vcc
	v_cmp_lt_i32_e32 vcc, 23, v204
	s_nop 1
	v_cndmask_b32_e32 v60, v185, v60, vcc
	v_cmp_lt_i32_e32 vcc, 24, v204
	s_nop 1
	v_cndmask_b32_e32 v61, v185, v61, vcc
	v_cmp_lt_i32_e32 vcc, 25, v204
	s_nop 1
	v_cndmask_b32_e32 v62, v185, v62, vcc
	v_cmp_lt_i32_e32 vcc, 26, v204
	s_nop 1
	v_cndmask_b32_e32 v63, v185, v63, vcc

; #define MFMA32(a, b, c) __builtin_amdgcn_mfma_f32_32x32x16_bf16((a), (b), (c), 0, 0, 0)
; DI float fexp2(float x) { return __builtin_amdgcn_exp2f(x); }
;     ...
;         auto pvm = [&](int j) {
; #pragma unroll
;           for (int st = 0; st < 2; ++st) {
;             u32x4 pp;
; #pragma unroll
;             for (int q = 0; q < 4; ++q) pp[q] = pk_bf16(s[j][8 * st + 2 * q], s[j][8 * st + 2 * q + 1]);
;             const bf16x8 pb = __builtin_bit_cast(bf16x8, pp);
; #pragma unroll
;             for (int dt = 0; dt < 2; ++dt) oacc[dt] = MFMA32(__builtin_bit_cast(bf16x8, vfr[st][dt]), pb, oacc[dt]);
;           }
;         };
;     ...
;           for (int j = 0; j < 2; ++j) {
;             ldv(j);
;             if (MODE == 2) {
; #pragma unroll
;               for (int g = 0; g < 4; ++g) {
;                 const f32x4 nf = *(const f32x4*)(Fl + buf * 64 + j * 32 + 8 * g + 4 * hh);
; #pragma unroll
;                 for (int e = 0; e < 4; ++e) s[j][4 * g + e] = fmaf(s[j][4 * g + e], c2, nf[e]);
;               }
;             }
;             if (diag) {
;               asm volatile("" ::: "memory");
; #pragma unroll
;               for (int i = 0; i < 16; ++i) s[j][i] = (j * 32 + 8 * (i >> 2) + (i & 3)) <= dq ? s[j][i] : -INFINITY;
;             }
;             float mt = fmaxf(s[j][0], s[j][1]);
; #pragma unroll
;             for (int i = 2; i < 16; ++i) mt = fmaxf(mt, s[j][i]);
;             mt = fmaxf(mt, __shfl_xor(mt, 32));
;             if (MODE == 1) mt *= c2;
;             const float cand = fmaxf(mrun, mt);
;             if (__any(cand > mrun + 8.f)) {
;               const float alpha = fexp2(mrun - cand);
;               mrun = cand; lsum *= alpha;
; #pragma unroll
;               for (int i = 0; i < 16; ++i) { oacc[0][i] *= alpha; oacc[1][i] *= alpha; }
;             }
;             const float nm = -mrun;
; #pragma unroll
;             for (int i = 0; i < 16; ++i) {
;               const float p = (MODE == 1) ? fexp2(fmaf(s[j][i], c2, nm)) : fexp2(s[j][i] + nm);
;               lsum += p; s[j][i] = p;
;             }
;             pvm(j);
.LBB0_840:
	v_fma_f32 v48, v48, s31, -v202
	v_exp_f32_e32 v210, v48
	v_fma_f32 v48, v49, s31, -v202
	v_exp_f32_e32 v212, v48
	v_fma_f32 v48, v50, s31, -v202
	v_exp_f32_e32 v213, v48
	v_fma_f32 v48, v51, s31, -v202
	v_exp_f32_e32 v214, v48
	v_fma_f32 v48, v52, s31, -v202
	v_exp_f32_e32 v215, v48
	v_fma_f32 v48, v53, s31, -v202
	v_exp_f32_e32 v216, v48
	v_fma_f32 v48, v54, s31, -v202
	v_exp_f32_e32 v217, v48
	v_fma_f32 v48, v55, s31, -v202
	v_exp_f32_e32 v218, v48
	v_fma_f32 v48, v56, s31, -v202
	v_exp_f32_e32 v219, v48
	v_fma_f32 v48, v57, s31, -v202
	v_exp_f32_e32 v220, v48
	v_fma_f32 v48, v58, s31, -v202
	v_exp_f32_e32 v221, v48
	v_fma_f32 v48, v59, s31, -v202
	v_exp_f32_e32 v222, v48
	v_fma_f32 v48, v60, s31, -v202
	v_exp_f32_e32 v203, v48
	v_fma_f32 v48, v61, s31, -v202
	v_exp_f32_e32 v208, v48
	v_fma_f32 v48, v62, s31, -v202
	v_exp_f32_e32 v209, v48
	v_fma_f32 v48, v63, s31, -v202
	v_exp_f32_e32 v211, v48
	v_cvt_pk_bf16_f32 v48, v210, v212
	v_cvt_pk_bf16_f32 v49, v213, v214
	v_cvt_pk_bf16_f32 v50, v215, v216
	v_cvt_pk_bf16_f32 v51, v217, v218
	s_nop 1
	v_mfma_f32_32x32x16_bf16 v[16:31], v[140:143], v[48:51], v[16:31]
	v_mfma_f32_32x32x16_bf16 v[0:15], v[136:139], v[48:51], v[0:15]
	v_cvt_pk_bf16_f32 v48, v219, v220
	v_cvt_pk_bf16_f32 v49, v221, v222
	v_cvt_pk_bf16_f32 v50, v203, v208
	v_cvt_pk_bf16_f32 v51, v209, v211
	s_nop 1
	v_mfma_f32_32x32x16_bf16 v[16:31], v[128:131], v[48:51], v[16:31]
	v_mfma_f32_32x32x16_bf16 v[0:15], v[132:135], v[48:51], v[0:15]
	ds_read_b128 v[60:63], v155 offset:26688
	ds_read_b128 v[52:55], v155 offset:26720
	ds_read_b128 v[56:59], v155 offset:31296
	ds_read_b128 v[48:51], v155 offset:31328
	s_and_saveexec_b64 s[8:9], s[46:47]
	s_cbranch_execz .LBB0_842
	v_cmp_lt_i32_e32 vcc, 31, v204
	s_nop 1
	v_cndmask_b32_e32 v32, v185, v32, vcc
	v_cmp_lt_i32_e32 vcc, 32, v204
	s_nop 1
	v_cndmask_b32_e32 v33, v185, v33, vcc
	v_cmp_lt_i32_e32 vcc, 33, v204
	s_nop 1
	v_cndmask_b32_e32 v34, v185, v34, vcc
	v_cmp_lt_i32_e32 vcc, 34, v204
	s_nop 1
	v_cndmask_b32_e32 v35, v185, v35, vcc
	v_cmp_lt_i32_e32 vcc, 39, v204
	s_nop 1
	v_cndmask_b32_e32 v36, v185, v36, vcc
	v_cmp_lt_i32_e32 vcc, 40, v204
	s_nop 1
	v_cndmask_b32_e32 v37, v185, v37, vcc
	v_cmp_lt_i32_e32 vcc, 41, v204
	s_nop 1
	v_cndmask_b32_e32 v38, v185, v38, vcc
	v_cmp_lt_i32_e32 vcc, 42, v204
	s_nop 1
	v_cndmask_b32_e32 v39, v185, v39, vcc
	v_cmp_lt_i32_e32 vcc, 47, v204
	s_nop 1
	v_cndmask_b32_e32 v40, v185, v40, vcc
	v_cmp_lt_i32_e32 vcc, 48, v204
	s_nop 1
	v_cndmask_b32_e32 v41, v185, v41, vcc
	v_cmp_lt_i32_e32 vcc, 49, v204
	s_nop 1
	v_cndmask_b32_e32 v42, v185, v42, vcc
	v_cmp_lt_i32_e32 vcc, 50, v204
	s_nop 1
	v_cndmask_b32_e32 v43, v185, v43, vcc
	v_cmp_lt_i32_e32 vcc, 55, v204
	s_nop 1
	v_cndmask_b32_e32 v44, v185, v44, vcc
	v_cmp_lt_i32_e32 vcc, 56, v204
	s_nop 1
	v_cndmask_b32_e32 v45, v185, v45, vcc
	v_cmp_lt_i32_e32 vcc, 57, v204
	s_nop 1
	v_cndmask_b32_e32 v46, v185, v46, vcc
	v_cmp_lt_i32_e32 vcc, 58, v204
	s_nop 1
	v_cndmask_b32_e32 v47, v185, v47, vcc

;     ...
;     auto lstore = [&](const u32x4 (&rk)[KCH], const u32x4 (&rv)[2], const float rf, int buf) {
;       bf16_t* kd = Kl + buf * 64 * KST + lkey * KST + lsub * 8;
;       *(u32x4*)kd = rk[0]; *(u32x4*)(kd + 32) = rk[1];
;       if (MODE == 1) *(u32x4*)(kd + 64) = rk[KCH - 1];
;       bf16_t* vd = Vl + buf * 64 * VST + lkey * VST + lsub * 8;
;       u32x2 lo, hi;
;       lo[0] = rv[0][0]; lo[1] = rv[0][1]; hi[0] = rv[0][2]; hi[1] = rv[0][3];
;       *(u32x2*)vd = lo; *(u32x2*)(vd + 4) = hi;
;       lo[0] = rv[1][0]; lo[1] = rv[1][1]; hi[0] = rv[1][2]; hi[1] = rv[1][3];
;       *(u32x2*)(vd + 32) = lo; *(u32x2*)(vd + 36) = hi;
;       if (MODE == 2 && t < 64) Fl[buf * 64 + t] = -rf * LOG2E;
;     };
;     ...
;       { const int kpre = kt > 1 ? kt - 2 : 0; if (PAR == 0) gload(rkA, rvA, rfA, kpre); else gload(rkB, rvB, rfB, kpre); }
;       if (kt * 64 <= wqmax && dry < 2) {
;         const bf16_t* Kb = Kl + buf * 64 * KST; const bf16_t* Vb = Vl + buf * 64 * VST;
;         f32x16 s[2];
; #pragma unroll
;         for (int i = 0; i < 16; ++i) { s[0][i] = 0.f; s[1][i] = 0.f; }
;         if (MODE == 0) {
; #pragma unroll
;           for (int ks = 0; ks < NKS; ++ks) {
;             const bf16x8 a0 = *(const bf16x8*)(Kb + r * KST + ks * 16 + 8 * hh);
;             const bf16x8 a1 = *(const bf16x8*)(Kb + (32 + r) * KST + ks * 16 + 8 * hh);
;             s[0] = MFMA32(a0, qf[ks], s[0]);
;             s[1] = MFMA32(a1, qf[ks], s[1]);
;           }
;         } else {
;           bf16x8 kf0[NKS], kf1[NKS];
; #pragma unroll
;           for (int ks = 0; ks < NKS; ++ks) kf0[ks] = *(const bf16x8*)(Kb + r * KST + ks * 16 + 8 * hh);
; #pragma unroll
;           for (int ks = 0; ks < NKS; ++ks) kf1[ks] = *(const bf16x8*)(Kb + (32 + r) * KST + ks * 16 + 8 * hh);
;           __builtin_amdgcn_sched_barrier(0);
; #pragma unroll
;           for (int ks = 0; ks < NKS; ++ks) s[0] = MFMA32(kf0[ks], qf[ks], s[0]);
; #pragma unroll
;           for (int ks = 0; ks < NKS; ++ks) s[1] = MFMA32(kf1[ks], qf[ks], s[1]);
;           __builtin_amdgcn_sched_barrier(0);
;         }
;         const int kbase = kt * 64 + 4 * hh;
;         u32x4 vfr[2][2];
;         auto ldv = [&](int j) {
; #pragma unroll
;           for (int st = 0; st < 2; ++st)
; #pragma unroll
;             for (int dt = 0; dt < 2; ++dt) {
;               const bf16_t* vp = Vb + (dt * 32 + r) * VST + j * 32 + 16 * st + 4 * hh;
.LBB0_846:
	s_or_b64 exec, exec, s[6:7]
	v_add_u32_e32 v32, 0x8c00, v154
	s_waitcnt vmcnt(9)
	ds_write_b128 v152, v[88:91] offset:13312
	s_waitcnt vmcnt(8)
	ds_write_b128 v152, v[92:95] offset:13376
	s_waitcnt vmcnt(7)
	ds_write_b128 v152, v[96:99] offset:13440
	s_waitcnt vmcnt(6)
	ds_write2_b64 v32, v[104:105], v[106:107] offset1:2
	v_add_u32_e32 v32, 0x8c40, v154
	s_cmp_lt_i32 s1, 1
	s_waitcnt vmcnt(5)
	ds_write2_b64 v32, v[100:101], v[102:103] offset1:2
	s_cbranch_scc1 .LBB0_852
	s_add_i32 s1, s1, -1
	s_max_u32 s5, s1, 2
	s_lshl_b32 s5, s5, 6
	s_add_i32 s6, s5, 0xffffff80
	v_add_u32_e32 v32, s6, v187
	v_min_i32_e32 v32, 0x200f, v32
	v_add_u32_e32 v32, s10, v32
	v_ashrrev_i32_e32 v33, 31, v32
	v_lshlrev_b64 v[34:35], 11, v[32:33]
	v_lshl_add_u64 v[34:35], v[170:171], 0, v[34:35]
	s_waitcnt lgkmcnt(0)
	s_barrier
	global_load_dwordx4 v[88:91], v[34:35], off
	global_load_dwordx4 v[92:95], v[34:35], off offset:64
	v_lshlrev_b64 v[32:33], 6, v[32:33]
	v_lshl_add_u64 v[32:33], v[158:159], 0, v[32:33]
	global_load_dwordx4 v[96:99], v[32:33], off
	s_ashr_i32 s7, s6, 31
	v_lshl_add_u64 v[32:33], s[6:7], 1, v[168:169]
	global_load_dwordx4 v[104:107], v[32:33], off
	global_load_dwordx4 v[100:103], v[32:33], off offset:64
	v_cmp_le_i32_e32 vcc, s4, v199
	s_and_saveexec_b64 s[6:7], vcc
	s_cbranch_execz .LBB0_833
	ds_read_b128 v[32:35], v153 offset:13312
	ds_read_b128 v[36:39], v153 offset:13344
	ds_read_b128 v[40:43], v153 offset:13376
	ds_read_b128 v[44:47], v153 offset:13408
	ds_read_b128 v[128:131], v153 offset:13440
	ds_read_b128 v[132:135], v153 offset:13472
	ds_read_b128 v[136:139], v153 offset:19968
	ds_read_b128 v[140:143], v153 offset:20000
	ds_read_b128 v[204:207], v153 offset:20032
	ds_read_b128 v[208:211], v153 offset:20064
	ds_read_b128 v[212:215], v153 offset:20096
	ds_read_b128 v[216:219], v153 offset:20128
	s_waitcnt lgkmcnt(11)
	v_mfma_f32_32x32x16_bf16 v[48:63], v[32:35], v[64:67], 0
	s_waitcnt lgkmcnt(10)
	v_mfma_f32_32x32x16_bf16 v[48:63], v[36:39], v[68:71], v[48:63]
	s_waitcnt lgkmcnt(9)
	v_mfma_f32_32x32x16_bf16 v[48:63], v[40:43], v[72:75], v[48:63]
	s_waitcnt lgkmcnt(8)
	v_mfma_f32_32x32x16_bf16 v[48:63], v[44:47], v[76:79], v[48:63]
	s_waitcnt lgkmcnt(5)
	v_mfma_f32_32x32x16_bf16 v[32:47], v[136:139], v[64:67], 0
	s_waitcnt lgkmcnt(4)
	v_mfma_f32_32x32x16_bf16 v[32:47], v[140:143], v[68:71], v[32:47]
	s_waitcnt lgkmcnt(3)
	v_mfma_f32_32x32x16_bf16 v[32:47], v[204:207], v[72:75], v[32:47]
	s_waitcnt lgkmcnt(2)
	v_mfma_f32_32x32x16_bf16 v[32:47], v[208:211], v[76:79], v[32:47]
	v_mfma_f32_32x32x16_bf16 v[48:63], v[128:131], v[80:83], v[48:63]
	s_waitcnt lgkmcnt(1)
	v_mfma_f32_32x32x16_bf16 v[32:47], v[212:215], v[80:83], v[32:47]
	v_mfma_f32_32x32x16_bf16 v[48:63], v[132:135], v[84:87], v[48:63]
	s_waitcnt lgkmcnt(0)
	v_mfma_f32_32x32x16_bf16 v[32:47], v[216:219], v[84:87], v[32:47]
	v_add_u32_e32 v205, 0x8800, v155
	v_add_u32_e32 v206, 0x9800, v155
	ds_read_b128 v[140:143], v155 offset:35840
	ds_read_b128 v[128:131], v155 offset:35872
	ds_read_b128 v[136:139], v155 offset:40448
	ds_read_b128 v[132:135], v155 offset:40480
	s_add_i32 s5, s4, 63
	v_cmp_gt_i32_e64 s[46:47], s5, v165
	s_and_saveexec_b64 s[8:9], s[46:47]
	s_cbranch_execz .LBB0_850
	v_cmp_lt_i32_e32 vcc, -1, v200
	s_nop 1
	v_cndmask_b32_e32 v48, v185, v48, vcc
	v_cmp_lt_i32_e32 vcc, 0, v200
	s_nop 1
	v_cndmask_b32_e32 v49, v185, v49, vcc
	v_cmp_lt_i32_e32 vcc, 1, v200
	s_nop 1
	v_cndmask_b32_e32 v50, v185, v50, vcc
	v_cmp_lt_i32_e32 vcc, 2, v200
	s_nop 1
	v_cndmask_b32_e32 v51, v185, v51, vcc
	v_cmp_lt_i32_e32 vcc, 7, v200
	s_nop 1
	v_cndmask_b32_e32 v52, v185, v52, vcc
	v_cmp_lt_i32_e32 vcc, 8, v200
	s_nop 1
	v_cndmask_b32_e32 v53, v185, v53, vcc
	v_cmp_lt_i32_e32 vcc, 9, v200
	s_nop 1
	v_cndmask_b32_e32 v54, v185, v54, vcc
	v_cmp_lt_i32_e32 vcc, 10, v200
	s_nop 1
	v_cndmask_b32_e32 v55, v185, v55, vcc
	v_cmp_lt_i32_e32 vcc, 15, v200
	s_nop 1
	v_cndmask_b32_e32 v56, v185, v56, vcc
	v_cmp_lt_i32_e32 vcc, 16, v200
	s_nop 1
	v_cndmask_b32_e32 v57, v185, v57, vcc
	v_cmp_lt_i32_e32 vcc, 17, v200
	s_nop 1
	v_cndmask_b32_e32 v58, v185, v58, vcc
	v_cmp_lt_i32_e32 vcc, 18, v200
	s_nop 1
	v_cndmask_b32_e32 v59, v185, v59, vcc
	v_cmp_lt_i32_e32 vcc, 23, v200
	s_nop 1
	v_cndmask_b32_e32 v60, v185, v60, vcc
	v_cmp_lt_i32_e32 vcc, 24, v200
	s_nop 1
	v_cndmask_b32_e32 v61, v185, v61, vcc
	v_cmp_lt_i32_e32 vcc, 25, v200
	s_nop 1
	v_cndmask_b32_e32 v62, v185, v62, vcc
	v_cmp_lt_i32_e32 vcc, 26, v200
	s_nop 1
	v_cndmask_b32_e32 v63, v185, v63, vcc

; #define MFMA32(a, b, c) __builtin_amdgcn_mfma_f32_32x32x16_bf16((a), (b), (c), 0, 0, 0)
; DI float fexp2(float x) { return __builtin_amdgcn_exp2f(x); }
;     ...
;         auto pvm = [&](int j) {
; #pragma unroll
;           for (int st = 0; st < 2; ++st) {
;             u32x4 pp;
; #pragma unroll
;             for (int q = 0; q < 4; ++q) pp[q] = pk_bf16(s[j][8 * st + 2 * q], s[j][8 * st + 2 * q + 1]);
;             const bf16x8 pb = __builtin_bit_cast(bf16x8, pp);
; #pragma unroll
;             for (int dt = 0; dt < 2; ++dt) oacc[dt] = MFMA32(__builtin_bit_cast(bf16x8, vfr[st][dt]), pb, oacc[dt]);
;           }
;         };
;     ...
;           for (int j = 0; j < 2; ++j) {
;             ldv(j);
;             if (MODE == 2) {
; #pragma unroll
;               for (int g = 0; g < 4; ++g) {
;                 const f32x4 nf = *(const f32x4*)(Fl + buf * 64 + j * 32 + 8 * g + 4 * hh);
; #pragma unroll
;                 for (int e = 0; e < 4; ++e) s[j][4 * g + e] = fmaf(s[j][4 * g + e], c2, nf[e]);
;               }
;             }
;             if (diag) {
;               asm volatile("" ::: "memory");
; #pragma unroll
;               for (int i = 0; i < 16; ++i) s[j][i] = (j * 32 + 8 * (i >> 2) + (i & 3)) <= dq ? s[j][i] : -INFINITY;
;             }
;             float mt = fmaxf(s[j][0], s[j][1]);
; #pragma unroll
;             for (int i = 2; i < 16; ++i) mt = fmaxf(mt, s[j][i]);
;             mt = fmaxf(mt, __shfl_xor(mt, 32));
;             if (MODE == 1) mt *= c2;
;             const float cand = fmaxf(mrun, mt);
;             if (__any(cand > mrun + 8.f)) {
;               const float alpha = fexp2(mrun - cand);
;               mrun = cand; lsum *= alpha;
; #pragma unroll
;               for (int i = 0; i < 16; ++i) { oacc[0][i] *= alpha; oacc[1][i] *= alpha; }
;             }
;             const float nm = -mrun;
; #pragma unroll
;             for (int i = 0; i < 16; ++i) {
;               const float p = (MODE == 1) ? fexp2(fmaf(s[j][i], c2, nm)) : fexp2(s[j][i] + nm);
;               lsum += p; s[j][i] = p;
;             }
;             pvm(j);
.LBB0_855:
	v_fma_f32 v48, v48, s31, -v202
	v_exp_f32_e32 v209, v48
	v_fma_f32 v48, v49, s31, -v202
	v_exp_f32_e32 v211, v48
	v_fma_f32 v48, v50, s31, -v202
	v_exp_f32_e32 v212, v48
	v_fma_f32 v48, v51, s31, -v202
	v_exp_f32_e32 v213, v48
	v_fma_f32 v48, v52, s31, -v202
	v_exp_f32_e32 v214, v48
	v_fma_f32 v48, v53, s31, -v202
	v_exp_f32_e32 v215, v48
	v_fma_f32 v48, v54, s31, -v202
	v_exp_f32_e32 v216, v48
	v_fma_f32 v48, v55, s31, -v202
	v_exp_f32_e32 v217, v48
	v_fma_f32 v48, v56, s31, -v202
	v_exp_f32_e32 v218, v48
	v_fma_f32 v48, v57, s31, -v202
	v_exp_f32_e32 v219, v48
	v_fma_f32 v48, v58, s31, -v202
	v_exp_f32_e32 v220, v48
	v_fma_f32 v48, v59, s31, -v202
	v_exp_f32_e32 v221, v48
	v_fma_f32 v48, v60, s31, -v202
	v_exp_f32_e32 v203, v48
	v_fma_f32 v48, v61, s31, -v202
	v_exp_f32_e32 v207, v48
	v_fma_f32 v48, v62, s31, -v202
	v_exp_f32_e32 v208, v48
	v_fma_f32 v48, v63, s31, -v202
	v_exp_f32_e32 v210, v48
	v_cvt_pk_bf16_f32 v48, v209, v211
	v_cvt_pk_bf16_f32 v49, v212, v213
	v_cvt_pk_bf16_f32 v50, v214, v215
	v_cvt_pk_bf16_f32 v51, v216, v217
	s_nop 1
	v_mfma_f32_32x32x16_bf16 v[16:31], v[140:143], v[48:51], v[16:31]
	v_mfma_f32_32x32x16_bf16 v[0:15], v[136:139], v[48:51], v[0:15]
	v_cvt_pk_bf16_f32 v48, v218, v219
	v_cvt_pk_bf16_f32 v49, v220, v221
	v_cvt_pk_bf16_f32 v50, v203, v207
	v_cvt_pk_bf16_f32 v51, v208, v210
	s_nop 1
	v_mfma_f32_32x32x16_bf16 v[16:31], v[128:131], v[48:51], v[16:31]
	v_mfma_f32_32x32x16_bf16 v[0:15], v[132:135], v[48:51], v[0:15]
	ds_read_b128 v[60:63], v155 offset:35904
	ds_read_b128 v[52:55], v155 offset:35936
	ds_read_b128 v[56:59], v155 offset:40512
	ds_read_b128 v[48:51], v155 offset:40544
	s_and_saveexec_b64 s[8:9], s[46:47]
	s_cbranch_execz .LBB0_830
	v_cmp_lt_i32_e32 vcc, 31, v200
	s_nop 1
	v_cndmask_b32_e32 v32, v185, v32, vcc
	v_cmp_lt_i32_e32 vcc, 32, v200
	s_nop 1
	v_cndmask_b32_e32 v33, v185, v33, vcc
	v_cmp_lt_i32_e32 vcc, 33, v200
	s_nop 1
	v_cndmask_b32_e32 v34, v185, v34, vcc
	v_cmp_lt_i32_e32 vcc, 34, v200
	s_nop 1
	v_cndmask_b32_e32 v35, v185, v35, vcc
	v_cmp_lt_i32_e32 vcc, 39, v200
	s_nop 1
	v_cndmask_b32_e32 v36, v185, v36, vcc
	v_cmp_lt_i32_e32 vcc, 40, v200
	s_nop 1
	v_cndmask_b32_e32 v37, v185, v37, vcc
	v_cmp_lt_i32_e32 vcc, 41, v200
	s_nop 1
	v_cndmask_b32_e32 v38, v185, v38, vcc
	v_cmp_lt_i32_e32 vcc, 42, v200
	s_nop 1
	v_cndmask_b32_e32 v39, v185, v39, vcc
	v_cmp_lt_i32_e32 vcc, 47, v200
	s_nop 1
	v_cndmask_b32_e32 v40, v185, v40, vcc
	v_cmp_lt_i32_e32 vcc, 48, v200
	s_nop 1
	v_cndmask_b32_e32 v41, v185, v41, vcc
	v_cmp_lt_i32_e32 vcc, 49, v200
	s_nop 1
	v_cndmask_b32_e32 v42, v185, v42, vcc
	v_cmp_lt_i32_e32 vcc, 50, v200
	s_nop 1
	v_cndmask_b32_e32 v43, v185, v43, vcc
	v_cmp_lt_i32_e32 vcc, 55, v200
	s_nop 1
	v_cndmask_b32_e32 v44, v185, v44, vcc
	v_cmp_lt_i32_e32 vcc, 56, v200
	s_nop 1
	v_cndmask_b32_e32 v45, v185, v45, vcc
	v_cmp_lt_i32_e32 vcc, 57, v200
	s_nop 1
	v_cndmask_b32_e32 v46, v185, v46, vcc
	v_cmp_lt_i32_e32 vcc, 58, v200
	s_nop 1
	v_cndmask_b32_e32 v47, v185, v47, vcc
	s_branch .LBB0_830
